# SwiGLU epilogue rewrite + mlstm_local state stores transposed through LDS into full-line 16B stores
# speedup vs baseline: 1.0207x; 1.0036x over previous
.LBB0_823:
	s_or_b64 exec, exec, s[54:55]
	s_mul_hi_i32 s13, s60, 0x1800
	s_mulk_i32 s60, 0x1800
	s_add_u32 s12, s10, s60
	s_addc_u32 s13, s11, s13
	s_lshl_b32 s16, s6, 7
	s_add_u32 s54, s12, s16
	s_addc_u32 s55, s13, 0
	v_mov_b32_e32 v73, v0
	v_lshl_add_u64 v[6:7], s[54:55], 0, v[72:73]
	v_mov_b32_e32 v77, v0
	v_lshl_add_u64 v[10:11], v[6:7], 0, v[76:77]
	v_mov_b32_e32 v75, v0
	global_load_dwordx4 v[14:17], v[10:11], off offset:1024
	v_lshl_add_u64 v[6:7], s[54:55], 0, v[74:75]
	v_lshl_add_u64 v[8:9], v[6:7], 0, v[76:77]
	global_load_dwordx4 v[18:21], v[8:9], off offset:1024
	global_load_dwordx4 v[22:25], v[10:11], off offset:1056
	global_load_dwordx4 v[26:29], v[8:9], off offset:1056
	global_load_dwordx4 v[30:33], v[10:11], off offset:1088
	global_load_dwordx4 v[34:37], v[8:9], off offset:1088
	v_sub_f32_e32 v6, v12, v13
	v_mul_f32_e32 v6, 0x3fb8aa3b, v6
	v_exp_f32_e32 v6, v6
	v_cmp_gt_u32_e64 s[54:55], s7, v106
	v_add_u32_e32 v42, 0x2400, v108
	v_add_u32_e32 v43, 0x2c00, v108
	v_cndmask_b32_e64 v7, 0, v6, s[52:53]
	ds_bpermute_b32 v6, v103, v7
	ds_bpermute_b32 v13, v104, v7
	v_cmp_gt_u32_e64 s[52:53], s7, v105
	s_lshl_b32 s6, s6, 8
	s_add_u32 s6, s12, s6
	s_addc_u32 s7, s13, 0
	s_add_u32 s6, s6, s22
	s_addc_u32 s7, s7, 0
	v_add_u32_e32 v54, s2, v107
	v_mov_b32_e32 v79, v0
	v_mov_b32_e32 v81, v0
	v_mov_b32_e32 v83, v0
	s_waitcnt vmcnt(5)
	v_cndmask_b32_e64 v40, 0, v15, s[52:53]
	v_cndmask_b32_e64 v14, 0, v14, s[52:53]
	s_waitcnt vmcnt(4)
	v_cndmask_b32_e64 v15, 0, v18, s[54:55]
	v_cndmask_b32_e64 v41, 0, v21, s[54:55]
	v_cndmask_b32_e64 v19, 0, v19, s[54:55]
	v_lshlrev_b32_e32 v12, 16, v14
	v_lshlrev_b32_e32 v7, 16, v15
	v_cndmask_b32_e64 v38, 0, v17, s[52:53]
	v_cndmask_b32_e64 v39, 0, v16, s[52:53]
	v_cndmask_b32_e64 v44, 0, v20, s[54:55]
	s_waitcnt vmcnt(3)
	v_cndmask_b32_e64 v45, 0, v25, s[52:53]
	v_cndmask_b32_e64 v48, 0, v22, s[52:53]
	s_waitcnt vmcnt(2)
	v_cndmask_b32_e64 v51, 0, v27, s[54:55]
	v_cndmask_b32_e64 v52, 0, v26, s[54:55]
	v_and_b32_e32 v15, 0xffff0000, v15
	v_and_b32_e32 v14, 0xffff0000, v14
	v_lshlrev_b32_e32 v17, 16, v19
	v_lshlrev_b32_e32 v16, 16, v40
	v_and_b32_e32 v18, 0xffff0000, v40
	v_lshlrev_b32_e32 v25, 16, v41
	v_and_b32_e32 v27, 0xffff0000, v41
	s_waitcnt lgkmcnt(0)
	v_pk_mul_f32 v[40:41], v[12:13], v[6:7]
	v_mov_b32_e32 v7, v13
	v_cndmask_b32_e64 v46, 0, v24, s[52:53]
	v_cndmask_b32_e64 v47, 0, v23, s[52:53]
	v_cndmask_b32_e64 v49, 0, v29, s[54:55]
	v_cndmask_b32_e64 v50, 0, v28, s[54:55]
	v_and_b32_e32 v19, 0xffff0000, v19
	v_lshlrev_b32_e32 v21, 16, v44
	v_lshlrev_b32_e32 v20, 16, v39
	v_and_b32_e32 v23, 0xffff0000, v44
	v_and_b32_e32 v22, 0xffff0000, v39
	v_lshlrev_b32_e32 v24, 16, v38
	v_and_b32_e32 v26, 0xffff0000, v38
	v_lshlrev_b32_e32 v29, 16, v52
	v_lshlrev_b32_e32 v28, 16, v48
	v_and_b32_e32 v39, 0xffff0000, v52
	v_and_b32_e32 v38, 0xffff0000, v48
	v_pk_mul_f32 v[12:13], v[6:7], v[14:15]
	v_pk_mul_f32 v[14:15], v[6:7], v[16:17]
	v_cvt_pk_bf16_f32 v40, v40, v41
	v_pk_mul_f32 v[16:17], v[6:7], v[18:19]
	v_pk_mul_f32 v[18:19], v[6:7], v[20:21]
	v_pk_mul_f32 v[20:21], v[6:7], v[22:23]
	v_pk_mul_f32 v[22:23], v[6:7], v[24:25]
	v_pk_mul_f32 v[24:25], v[6:7], v[26:27]
	v_pk_mul_f32 v[26:27], v[6:7], v[28:29]
	v_pk_mul_f32 v[28:29], v[6:7], v[38:39]
	v_cvt_pk_bf16_f32 v12, v12, v13
	v_cvt_pk_bf16_f32 v13, v14, v15
	v_cvt_pk_bf16_f32 v14, v16, v17
	v_cvt_pk_bf16_f32 v15, v18, v19
	v_cvt_pk_bf16_f32 v16, v20, v21
	v_cvt_pk_bf16_f32 v17, v22, v23
	v_cvt_pk_bf16_f32 v18, v24, v25
	v_cvt_pk_bf16_f32 v19, v26, v27
	v_cvt_pk_bf16_f32 v20, v28, v29
	ds_write2_b32 v42, v40, v12 offset1:36
	ds_write2_b32 v42, v13, v14 offset0:72 offset1:108
	ds_write2_b32 v42, v15, v16 offset0:144 offset1:180
	ds_write_b32 v108, v17 offset:10080
	ds_write_b32 v109, v18 offset:9216
	ds_write2_b32 v43, v19, v20 offset0:64 offset1:100
	v_lshlrev_b32_e32 v13, 16, v51
	v_lshlrev_b32_e32 v12, 16, v47
	v_pk_mul_f32 v[12:13], v[6:7], v[12:13]
	s_waitcnt vmcnt(1)
	v_cndmask_b32_e64 v28, 0, v31, s[52:53]
	v_cvt_pk_bf16_f32 v14, v12, v13
	v_and_b32_e32 v13, 0xffff0000, v51
	v_and_b32_e32 v12, 0xffff0000, v47
	v_pk_mul_f32 v[12:13], v[6:7], v[12:13]
	s_waitcnt vmcnt(0)
	v_cndmask_b32_e64 v22, 0, v35, s[54:55]
	v_cvt_pk_bf16_f32 v15, v12, v13
	ds_write2_b32 v43, v14, v15 offset0:136 offset1:172
	v_lshlrev_b32_e32 v15, 16, v50
	v_lshlrev_b32_e32 v14, 16, v46
	global_load_dwordx4 v[10:13], v[10:11], off offset:1120
	v_pk_mul_f32 v[18:19], v[6:7], v[14:15]
	global_load_dwordx4 v[14:17], v[8:9], off offset:1120
	v_and_b32_e32 v9, 0xffff0000, v50
	v_and_b32_e32 v8, 0xffff0000, v46
	v_pk_mul_f32 v[8:9], v[6:7], v[8:9]
	v_cvt_pk_bf16_f32 v18, v18, v19
	v_cvt_pk_bf16_f32 v8, v8, v9
	ds_write2_b32 v43, v18, v8 offset0:208 offset1:244
	v_lshlrev_b32_e32 v9, 16, v49
	v_lshlrev_b32_e32 v8, 16, v45
	v_pk_mul_f32 v[8:9], v[6:7], v[8:9]
	v_cndmask_b32_e64 v18, 0, v30, s[52:53]
	v_cvt_pk_bf16_f32 v8, v8, v9
	ds_write_b32 v108, v8 offset:12384
	v_and_b32_e32 v9, 0xffff0000, v49
	v_and_b32_e32 v8, 0xffff0000, v45
	v_pk_mul_f32 v[8:9], v[6:7], v[8:9]
	v_cndmask_b32_e64 v19, 0, v34, s[54:55]
	v_cvt_pk_bf16_f32 v8, v8, v9
	ds_write_b32 v110, v8 offset:9216
	v_lshlrev_b32_e32 v9, 16, v19
	v_lshlrev_b32_e32 v8, 16, v18
	v_pk_mul_f32 v[8:9], v[6:7], v[8:9]
	v_add_u32_e32 v31, 0x3400, v108
	v_cvt_pk_bf16_f32 v20, v8, v9
	v_and_b32_e32 v9, 0xffff0000, v19
	v_and_b32_e32 v8, 0xffff0000, v18
	v_pk_mul_f32 v[8:9], v[6:7], v[8:9]
	v_cndmask_b32_e64 v27, 0, v32, s[52:53]
	v_cvt_pk_bf16_f32 v8, v8, v9
	ds_write2_b32 v31, v20, v8 offset0:128 offset1:164
	v_lshlrev_b32_e32 v9, 16, v22
	v_lshlrev_b32_e32 v8, 16, v28
	v_pk_mul_f32 v[8:9], v[6:7], v[8:9]
	v_cndmask_b32_e64 v29, 0, v37, s[54:55]
	v_cvt_pk_bf16_f32 v32, v8, v9
	v_lshl_add_u64 v[8:9], s[6:7], 0, v[72:73]
	v_lshl_add_u64 v[34:35], v[8:9], 0, v[76:77]
	v_and_b32_e32 v9, 0xffff0000, v22
	v_lshl_add_u64 v[22:23], s[6:7], 0, v[74:75]
	v_cndmask_b32_e64 v30, 0, v36, s[54:55]
	global_load_dwordx4 v[18:21], v[34:35], off offset:2048
	v_lshl_add_u64 v[36:37], v[22:23], 0, v[76:77]
	global_load_dwordx4 v[22:25], v[36:37], off offset:2048
	v_and_b32_e32 v8, 0xffff0000, v28
	v_pk_mul_f32 v[8:9], v[6:7], v[8:9]
	v_cndmask_b32_e64 v26, 0, v33, s[52:53]
	v_cvt_pk_bf16_f32 v8, v8, v9
	ds_write2_b32 v31, v32, v8 offset0:200 offset1:236
	v_lshlrev_b32_e32 v9, 16, v30
	v_lshlrev_b32_e32 v8, 16, v27
	v_pk_mul_f32 v[8:9], v[6:7], v[8:9]
	v_add_u32_e32 v41, 0x4000, v108
	v_cvt_pk_bf16_f32 v28, v8, v9
	v_and_b32_e32 v9, 0xffff0000, v30
	v_and_b32_e32 v8, 0xffff0000, v27
	v_pk_mul_f32 v[8:9], v[6:7], v[8:9]
	s_mul_i32 s6, s58, 0x4400
	v_cvt_pk_bf16_f32 v8, v8, v9
	v_add_u32_e32 v9, 0x3800, v108
	ds_write2_b32 v9, v28, v8 offset0:16 offset1:52
	v_lshlrev_b32_e32 v9, 16, v29
	v_lshlrev_b32_e32 v8, 16, v26
	v_pk_mul_f32 v[8:9], v[6:7], v[8:9]
	s_mul_hi_i32 s7, s58, 0x4400
	v_cvt_pk_bf16_f32 v8, v8, v9
	ds_write_b32 v108, v8 offset:14688
	v_and_b32_e32 v9, 0xffff0000, v29
	v_and_b32_e32 v8, 0xffff0000, v26
	v_pk_mul_f32 v[8:9], v[6:7], v[8:9]
	global_load_dwordx4 v[26:29], v[34:35], off offset:2080
	v_cvt_pk_bf16_f32 v8, v8, v9
	ds_write_b32 v111, v8 offset:9216
	s_add_u32 s6, s24, s6
	s_addc_u32 s7, s25, s7
	s_waitcnt vmcnt(4)
	v_cndmask_b32_e64 v31, 0, v10, s[52:53]
	v_cndmask_b32_e64 v38, 0, v13, s[52:53]
	s_waitcnt vmcnt(3)
	v_cndmask_b32_e64 v14, 0, v14, s[54:55]
	v_cndmask_b32_e64 v39, 0, v12, s[52:53]
	v_lshlrev_b32_e32 v13, 16, v14
	v_lshlrev_b32_e32 v12, 16, v31
	v_pk_mul_f32 v[12:13], v[6:7], v[12:13]
	v_cndmask_b32_e64 v32, 0, v16, s[54:55]
	v_cvt_pk_bf16_f32 v16, v12, v13
	v_and_b32_e32 v13, 0xffff0000, v14
	v_and_b32_e32 v12, 0xffff0000, v31
	v_cndmask_b32_e64 v30, 0, v11, s[52:53]
	global_load_dwordx4 v[8:11], v[36:37], off offset:2080
	v_pk_mul_f32 v[12:13], v[6:7], v[12:13]
	v_cndmask_b32_e64 v15, 0, v15, s[54:55]
	v_cvt_pk_bf16_f32 v12, v12, v13
	v_add_u32_e32 v13, 0x3c00, v108
	v_cndmask_b32_e64 v40, 0, v17, s[54:55]
	ds_write2_b32 v13, v16, v12 offset0:192 offset1:228
	v_lshlrev_b32_e32 v13, 16, v15
	v_lshlrev_b32_e32 v12, 16, v30
	v_lshlrev_b32_e32 v17, 16, v32
	v_lshlrev_b32_e32 v16, 16, v39
	v_pk_mul_f32 v[12:13], v[6:7], v[12:13]
	v_pk_mul_f32 v[16:17], v[6:7], v[16:17]
	v_cvt_pk_bf16_f32 v14, v12, v13
	v_and_b32_e32 v13, 0xffff0000, v15
	v_and_b32_e32 v12, 0xffff0000, v30
	v_cvt_pk_bf16_f32 v42, v16, v17
	v_and_b32_e32 v17, 0xffff0000, v32
	v_and_b32_e32 v16, 0xffff0000, v39
	v_pk_mul_f32 v[12:13], v[6:7], v[12:13]
	v_pk_mul_f32 v[16:17], v[6:7], v[16:17]
	v_cvt_pk_bf16_f32 v12, v12, v13
	v_cvt_pk_bf16_f32 v16, v16, v17
	ds_write2_b32 v41, v14, v12 offset0:8 offset1:44
	global_load_dwordx4 v[12:15], v[34:35], off offset:2112
	ds_write2_b32 v41, v42, v16 offset0:80 offset1:116
	v_lshlrev_b32_e32 v17, 16, v40
	v_lshlrev_b32_e32 v16, 16, v38
	global_load_dwordx4 v[30:33], v[36:37], off offset:2112
	v_pk_mul_f32 v[16:17], v[6:7], v[16:17]
	s_waitcnt vmcnt(4)
	v_cndmask_b32_e64 v39, 0, v23, s[54:55]
	v_cvt_pk_bf16_f32 v16, v16, v17
	ds_write_b32 v108, v16 offset:16992
	v_and_b32_e32 v17, 0xffff0000, v40
	v_and_b32_e32 v16, 0xffff0000, v38
	v_pk_mul_f32 v[6:7], v[6:7], v[16:17]
	v_cndmask_b32_e64 v16, 0, v18, s[52:53]
	v_cvt_pk_bf16_f32 v6, v6, v7
	v_cndmask_b32_e64 v17, 0, v22, s[54:55]
	v_and_b32_e32 v18, 0xffff, v16
	v_lshrrev_b32_e32 v16, 16, v16
	ds_write_b32 v112, v6 offset:9216
	v_cndmask_b32_e64 v6, 0, v21, s[52:53]
	v_cndmask_b32_e64 v7, 0, v20, s[52:53]
	v_cndmask_b32_e64 v38, 0, v19, s[52:53]
	v_lshl_or_b32 v20, v17, 16, v18
	v_and_or_b32 v21, v17, s3, v16
	global_load_dwordx4 v[16:19], v[34:35], off offset:2144
	ds_write2_b32 v108, v20, v21 offset1:36
	v_and_b32_e32 v20, 0xffff, v38
	v_lshl_or_b32 v34, v39, 16, v20
	global_load_dwordx4 v[20:23], v[36:37], off offset:2144
	v_lshrrev_b32_e32 v35, 16, v38
	v_and_or_b32 v35, v39, s3, v35
	v_cndmask_b32_e64 v24, 0, v24, s[54:55]
	ds_write2_b32 v108, v34, v35 offset0:72 offset1:108
	v_and_b32_e32 v34, 0xffff, v7
	v_lshrrev_b32_e32 v7, 16, v7
	v_lshl_or_b32 v34, v24, 16, v34
	v_and_or_b32 v7, v24, s3, v7
	v_cndmask_b32_e64 v25, 0, v25, s[54:55]
	ds_write2_b32 v108, v34, v7 offset0:144 offset1:180
	v_and_b32_e32 v7, 0xffff, v6
	v_lshrrev_b32_e32 v6, 16, v6
	v_lshl_or_b32 v7, v25, 16, v7
	v_and_or_b32 v6, v25, s3, v6
	s_waitcnt vmcnt(5)
	v_cndmask_b32_e64 v25, 0, v26, s[52:53]
	v_and_b32_e32 v26, 0xffff, v25
	v_lshrrev_b32_e32 v25, 16, v25
	v_cndmask_b32_e64 v24, 0, v27, s[52:53]
	ds_write_b32 v108, v7 offset:864
	ds_write_b32 v109, v6
	v_cndmask_b32_e64 v7, 0, v28, s[52:53]
	v_cndmask_b32_e64 v6, 0, v29, s[52:53]
	s_waitcnt vmcnt(4)
	v_cndmask_b32_e64 v8, 0, v8, s[54:55]
	v_lshl_or_b32 v26, v8, 16, v26
	v_and_or_b32 v8, v8, s3, v25
	v_add_u32_e32 v25, 0x800, v108
	v_cndmask_b32_e64 v9, 0, v9, s[54:55]
	ds_write2_b32 v25, v26, v8 offset0:64 offset1:100
	v_and_b32_e32 v8, 0xffff, v24
	v_lshrrev_b32_e32 v24, 16, v24
	v_lshl_or_b32 v8, v9, 16, v8
	v_and_or_b32 v9, v9, s3, v24
	v_cndmask_b32_e64 v10, 0, v10, s[54:55]
	ds_write2_b32 v25, v8, v9 offset0:136 offset1:172
	v_and_b32_e32 v8, 0xffff, v7
	v_lshrrev_b32_e32 v7, 16, v7
	v_lshl_or_b32 v8, v10, 16, v8
	v_and_or_b32 v7, v10, s3, v7
	v_cndmask_b32_e64 v11, 0, v11, s[54:55]
	ds_write2_b32 v25, v8, v7 offset0:208 offset1:244
	v_and_b32_e32 v7, 0xffff, v6
	v_lshl_or_b32 v7, v11, 16, v7
	ds_write_b32 v108, v7 offset:3168
	v_lshrrev_b32_e32 v6, 16, v6
	v_and_or_b32 v6, v11, s3, v6
	ds_write_b32 v110, v6
	s_waitcnt vmcnt(3)
	v_cndmask_b32_e64 v9, 0, v12, s[52:53]
	v_cndmask_b32_e64 v7, 0, v14, s[52:53]
	v_cndmask_b32_e64 v8, 0, v13, s[52:53]
	v_and_b32_e32 v14, 0xffff, v9
	s_waitcnt vmcnt(2)
	v_cndmask_b32_e64 v13, 0, v30, s[54:55]
	v_lshrrev_b32_e32 v9, 16, v9
	v_lshl_or_b32 v14, v13, 16, v14
	v_and_or_b32 v9, v13, s3, v9
	v_add_u32_e32 v13, 0x1000, v108
	v_cndmask_b32_e64 v12, 0, v31, s[54:55]
	ds_write2_b32 v13, v14, v9 offset0:128 offset1:164
	v_and_b32_e32 v9, 0xffff, v8
	v_lshrrev_b32_e32 v8, 16, v8
	v_lshl_or_b32 v9, v12, 16, v9
	v_and_or_b32 v8, v12, s3, v8
	v_cndmask_b32_e64 v11, 0, v32, s[54:55]
	ds_write2_b32 v13, v9, v8 offset0:200 offset1:236
	v_and_b32_e32 v8, 0xffff, v7
	v_lshrrev_b32_e32 v7, 16, v7
	v_lshl_or_b32 v8, v11, 16, v8
	v_and_or_b32 v7, v11, s3, v7
	v_add_u32_e32 v9, 0x1400, v108
	v_cndmask_b32_e64 v6, 0, v15, s[52:53]
	ds_write2_b32 v9, v8, v7 offset0:16 offset1:52
	v_cndmask_b32_e64 v10, 0, v33, s[54:55]
	s_waitcnt vmcnt(1)
	v_cndmask_b32_e64 v9, 0, v16, s[52:53]
	v_and_b32_e32 v7, 0xffff, v6
	v_lshrrev_b32_e32 v6, 16, v6
	v_and_b32_e32 v14, 0xffff, v9
	s_waitcnt vmcnt(0)
	v_cndmask_b32_e64 v13, 0, v20, s[54:55]
	v_lshrrev_b32_e32 v9, 16, v9
	v_lshl_or_b32 v7, v10, 16, v7
	v_and_or_b32 v6, v10, s3, v6
	v_cndmask_b32_e64 v8, 0, v17, s[52:53]
	v_lshl_or_b32 v14, v13, 16, v14
	v_and_or_b32 v9, v13, s3, v9
	v_add_u32_e32 v13, 0x1800, v108
	ds_write_b32 v108, v7 offset:5472
	ds_write_b32 v111, v6
	v_cndmask_b32_e64 v12, 0, v21, s[54:55]
	ds_write2_b32 v13, v14, v9 offset0:192 offset1:228
	v_and_b32_e32 v9, 0xffff, v8
	v_lshrrev_b32_e32 v8, 16, v8
	v_cndmask_b32_e64 v7, 0, v18, s[52:53]
	v_lshl_or_b32 v9, v12, 16, v9
	v_and_or_b32 v8, v12, s3, v8
	v_add_u32_e32 v12, 0x1c00, v108
	v_cndmask_b32_e64 v11, 0, v22, s[54:55]
	ds_write2_b32 v12, v9, v8 offset0:8 offset1:44
	v_and_b32_e32 v8, 0xffff, v7
	v_lshrrev_b32_e32 v7, 16, v7
	v_cndmask_b32_e64 v6, 0, v19, s[52:53]
	v_lshl_or_b32 v8, v11, 16, v8
	v_and_or_b32 v7, v11, s3, v7
	v_cndmask_b32_e64 v10, 0, v23, s[54:55]
	ds_write2_b32 v12, v8, v7 offset0:80 offset1:116
	v_and_b32_e32 v7, 0xffff, v6
	v_lshrrev_b32_e32 v6, 16, v6
	v_lshl_or_b32 v7, v10, 16, v7
	v_and_or_b32 v6, v10, s3, v6
	ds_write_b32 v108, v7 offset:7776
	ds_write_b32 v112, v6
	ds_read_b128 v[6:9], v54 offset:9216
	ds_read_b128 v[10:13], v54
	ds_read_b128 v[14:17], v54 offset:9280
	ds_read_b128 v[18:21], v54 offset:64
	ds_read_b128 v[26:29], v54 offset:2304
	ds_read_b128 v[30:33], v54 offset:4608
	ds_read_b128 v[42:45], v113
	ds_read_b128 v[84:87], v113 offset:64
	ds_read_b128 v[50:53], v54 offset:11520
	ds_read_b128 v[54:57], v54 offset:13824
	s_waitcnt lgkmcnt(1)
	v_mfma_f32_16x16x32_bf16 v[58:61], v[50:53], v[10:13], 0
	v_mfma_f32_16x16x32_bf16 v[88:91], v[50:53], v[26:29], 0
	v_mfma_f32_16x16x32_bf16 v[116:119], v[50:53], v[30:33], 0
	v_mfma_f32_16x16x32_bf16 v[120:123], v[50:53], v[42:45], 0
	v_mfma_f32_16x16x32_bf16 v[124:127], v[50:53], v[2:5], 0
	ds_read_b128 v[50:53], v113 offset:9216
	ds_read_b128 v[148:151], v113 offset:9280
	ds_read_b128 v[176:179], v114 offset:2304
	ds_read_b128 v[180:183], v114 offset:4608
	v_mfma_f32_16x16x32_bf16 v[22:25], v[6:9], v[10:13], 0
	v_mfma_f32_16x16x32_bf16 v[34:37], v[6:9], v[26:29], 0
	v_mfma_f32_16x16x32_bf16 v[38:41], v[6:9], v[30:33], 0
	v_mfma_f32_16x16x32_bf16 v[46:49], v[6:9], v[42:45], 0
	v_mfma_f32_16x16x32_bf16 v[6:9], v[6:9], v[2:5], 0
	v_mfma_f32_16x16x32_bf16 v[172:175], v[14:17], v[18:21], v[22:25]
	s_waitcnt lgkmcnt(1)
	v_mfma_f32_16x16x32_bf16 v[184:187], v[14:17], v[176:179], v[34:37]
	s_waitcnt lgkmcnt(0)
	v_mfma_f32_16x16x32_bf16 v[188:191], v[14:17], v[180:183], v[38:41]
	v_mfma_f32_16x16x32_bf16 v[192:195], v[14:17], v[84:87], v[46:49]
	v_mfma_f32_16x16x32_bf16 v[66:69], v[14:17], v[2:5], v[6:9]
	s_nop 2
	ds_read_b128 v[6:9], v114 offset:11520
	ds_read_b128 v[14:17], v114 offset:13824
	v_mfma_f32_16x16x32_bf16 v[128:131], v[54:57], v[10:13], 0
	v_mfma_f32_16x16x32_bf16 v[140:143], v[54:57], v[42:45], 0
	v_mfma_f32_16x16x32_bf16 v[10:13], v[50:53], v[10:13], 0
	v_mfma_f32_16x16x32_bf16 v[164:167], v[50:53], v[42:45], 0
	v_mfma_f32_16x16x32_bf16 v[132:135], v[54:57], v[26:29], 0
	v_mfma_f32_16x16x32_bf16 v[136:139], v[54:57], v[30:33], 0
	v_mfma_f32_16x16x32_bf16 v[144:147], v[54:57], v[2:5], 0
	v_mfma_f32_16x16x32_bf16 v[152:155], v[50:53], v[26:29], 0
	v_mfma_f32_16x16x32_bf16 v[156:159], v[50:53], v[30:33], 0
	v_mfma_f32_16x16x32_bf16 v[168:171], v[50:53], v[2:5], 0
	s_waitcnt lgkmcnt(1)
	v_mfma_f32_16x16x32_bf16 v[62:65], v[6:9], v[18:21], v[58:61]
	v_mfma_f32_16x16x32_bf16 v[58:61], v[6:9], v[176:179], v[88:91]
	v_mfma_f32_16x16x32_bf16 v[50:53], v[6:9], v[84:87], v[120:123]
	s_waitcnt lgkmcnt(0)
	v_mfma_f32_16x16x32_bf16 v[30:33], v[14:17], v[84:87], v[140:143]
	v_mfma_f32_16x16x32_bf16 v[22:25], v[148:151], v[18:21], v[10:13]
	v_mfma_f32_16x16x32_bf16 v[10:13], v[148:151], v[84:87], v[164:167]
	v_mfma_f32_16x16x32_bf16 v[54:57], v[6:9], v[180:183], v[116:119]
	v_mfma_f32_16x16x32_bf16 v[46:49], v[6:9], v[2:5], v[124:127]
	v_mfma_f32_16x16x32_bf16 v[42:45], v[14:17], v[18:21], v[128:131]
	v_mfma_f32_16x16x32_bf16 v[38:41], v[14:17], v[176:179], v[132:135]
	v_mfma_f32_16x16x32_bf16 v[34:37], v[14:17], v[180:183], v[136:139]
	v_mfma_f32_16x16x32_bf16 v[26:29], v[14:17], v[2:5], v[144:147]
	v_mfma_f32_16x16x32_bf16 v[18:21], v[148:151], v[176:179], v[152:155]
	v_mfma_f32_16x16x32_bf16 v[14:17], v[148:151], v[180:183], v[156:159]
	v_mfma_f32_16x16x32_bf16 v[6:9], v[148:151], v[2:5], v[168:171]
	v_and_b32_e32 v200, 15, v207
	v_lshrrev_b32_e32 v201, 4, v207
	v_mul_u32_u24_e32 v202, 0x90, v200
	v_lshl_add_u32 v202, v201, 3, v202
	v_add_u32_e32 v202, s2, v202
	v_lshrrev_b32_e32 v203, 3, v207
	v_and_b32_e32 v204, 7, v207
	v_mul_u32_u24_e32 v203, 0x90, v203
	v_lshl_add_u32 v203, v204, 4, v203
	v_add_u32_e32 v203, s2, v203
	s_lshl_b32 s16, s22, 6
	v_lshlrev_b32_e32 v198, 4, v207
	v_add_u32_e32 v198, s16, v198
	v_mov_b32_e32 v199, 0
	v_lshl_add_u64 v[196:197], s[6:7], 0, v[198:199]
	v_lshl_add_u64 v[88:89], s[6:7], 0, v[78:79]
	s_mov_b64 s[6:7], 0x4000
	v_lshl_add_u64 v[84:85], v[88:89], 0, s[6:7]
	s_mov_b64 s[6:7], 0x1000
	v_lshl_add_u64 v[204:205], v[196:197], 0, s[6:7]
	v_cvt_pk_bf16_f32 v172, v172, v173
	v_cvt_pk_bf16_f32 v173, v174, v175
	ds_write_b64 v202, v[172:173]
	v_cvt_pk_bf16_f32 v184, v184, v185
	v_cvt_pk_bf16_f32 v185, v186, v187
	ds_write_b64 v202, v[184:185] offset:2304
	v_cvt_pk_bf16_f32 v188, v188, v189
	v_cvt_pk_bf16_f32 v189, v190, v191
	ds_write_b64 v202, v[188:189] offset:4608
	v_cvt_pk_bf16_f32 v192, v192, v193
	v_cvt_pk_bf16_f32 v193, v194, v195
	ds_write_b64 v202, v[192:193] offset:6912
	v_cvt_pk_bf16_f32 v62, v62, v63
	v_cvt_pk_bf16_f32 v63, v64, v65
	ds_write_b64 v202, v[62:63] offset:32
	v_cvt_pk_bf16_f32 v58, v58, v59
	v_cvt_pk_bf16_f32 v59, v60, v61
	ds_write_b64 v202, v[58:59] offset:2336
	v_cvt_pk_bf16_f32 v54, v54, v55
	v_cvt_pk_bf16_f32 v55, v56, v57
	ds_write_b64 v202, v[54:55] offset:4640
	v_cvt_pk_bf16_f32 v50, v50, v51
	v_cvt_pk_bf16_f32 v51, v52, v53
	ds_write_b64 v202, v[50:51] offset:6944
	v_cvt_pk_bf16_f32 v42, v42, v43
	v_cvt_pk_bf16_f32 v43, v44, v45
	ds_write_b64 v202, v[42:43] offset:64
	v_cvt_pk_bf16_f32 v38, v38, v39
	v_cvt_pk_bf16_f32 v39, v40, v41
	ds_write_b64 v202, v[38:39] offset:2368
	v_cvt_pk_bf16_f32 v34, v34, v35
	v_cvt_pk_bf16_f32 v35, v36, v37
	ds_write_b64 v202, v[34:35] offset:4672
	v_cvt_pk_bf16_f32 v30, v30, v31
	v_cvt_pk_bf16_f32 v31, v32, v33
	ds_write_b64 v202, v[30:31] offset:6976
	v_cvt_pk_bf16_f32 v22, v22, v23
	v_cvt_pk_bf16_f32 v23, v24, v25
	ds_write_b64 v202, v[22:23] offset:96
	v_cvt_pk_bf16_f32 v18, v18, v19
	v_cvt_pk_bf16_f32 v19, v20, v21
	ds_write_b64 v202, v[18:19] offset:2400
	v_cvt_pk_bf16_f32 v14, v14, v15
	v_cvt_pk_bf16_f32 v15, v16, v17
	ds_write_b64 v202, v[14:15] offset:4704
	v_cvt_pk_bf16_f32 v10, v10, v11
	v_cvt_pk_bf16_f32 v11, v12, v13
	ds_write_b64 v202, v[10:11] offset:7008
	s_waitcnt lgkmcnt(0)
	ds_read_b128 v[208:211], v203
	ds_read_b128 v[212:215], v203 offset:1152
	ds_read_b128 v[216:219], v203 offset:2304
	ds_read_b128 v[220:223], v203 offset:3456
	ds_read_b128 v[224:227], v203 offset:4608
	ds_read_b128 v[228:231], v203 offset:5760
	ds_read_b128 v[172:175], v203 offset:6912
	ds_read_b128 v[184:187], v203 offset:8064
	s_waitcnt lgkmcnt(7)
	global_store_dwordx4 v[196:197], v[208:211], off
	s_waitcnt lgkmcnt(6)
	global_store_dwordx4 v[196:197], v[212:215], off offset:1024
	s_waitcnt lgkmcnt(5)
	global_store_dwordx4 v[196:197], v[216:219], off offset:2048
	s_waitcnt lgkmcnt(4)
	global_store_dwordx4 v[196:197], v[220:223], off offset:3072
	s_waitcnt lgkmcnt(3)
	global_store_dwordx4 v[204:205], v[224:227], off
	s_waitcnt lgkmcnt(2)
	global_store_dwordx4 v[204:205], v[228:231], off offset:1024
	s_waitcnt lgkmcnt(1)
	global_store_dwordx4 v[204:205], v[172:175], off offset:2048
	s_waitcnt lgkmcnt(0)
	global_store_dwordx4 v[204:205], v[184:187], off offset:3072
	s_and_saveexec_b64 s[52:53], s[50:51]
	s_cbranch_execz .LBB0_816
	v_cvt_pk_bf16_f32 v66, v66, v67
	v_cvt_pk_bf16_f32 v67, v68, v69
	global_store_dwordx2 v[84:85], v[66:67], off
	v_cvt_pk_bf16_f32 v46, v46, v47
	v_cvt_pk_bf16_f32 v47, v48, v49
	global_store_dwordx2 v[84:85], v[46:47], off offset:32
	v_cvt_pk_bf16_f32 v26, v26, v27
	v_cvt_pk_bf16_f32 v27, v28, v29
	global_store_dwordx2 v[84:85], v[26:27], off offset:64
	v_cvt_pk_bf16_f32 v6, v6, v7
	v_cvt_pk_bf16_f32 v7, v8, v9
	global_store_dwordx2 v[84:85], v[6:7], off offset:96
	s_branch .LBB0_816
